# v100 with in-proj XCD tile mapping NP=2 (W slice L2 resident) instead of NP=1
# baseline (speedup 1.0000x reference)
.LBB0_121:
	s_andn2_saveexec_b64 s[48:49], s[48:49]
	s_cbranch_execz .LBB0_112
	s_mov_b32 s25, 0x55555556
	v_mul_hi_i32 v2, v0, s25
	v_lshrrev_b32_e32 v2, 1, v2
	v_lshrrev_b32_e32 v1, 1, v16
	s_movk_i32 s25, 36
	v_mad_u32_u24 v4, v1, s25, v2
	v_mul_u32_u24_e32 v2, 6, v2
	v_sub_u32_e32 v0, v0, v2
	v_and_b32_e32 v1, 1, v16
	v_mad_u32_u24 v0, v1, 6, v0
	v_lshl_or_b32 v1, v4, 6, v0
	s_andn2_b64 s[46:47], s[46:47], exec
	s_branch .LBB0_112
